# speedup vs baseline: 1.0872x; 1.0025x over previous
; template <int DQK>
; __device__ __forceinline__ void qkt(f32x16& p0, f32x16& p1, const bf16* Ks, const bf16x8* qr, int r32, int hi, int k0, int L) {
;   p0 = f32x16{}; p1 = f32x16{};
; #pragma unroll
;   for (int d0 = 0; d0 < DQK / 16; ++d0) { int cb = (d0 * 16 + hi * 8) * 2;
;     bf16x8 b0 = *reinterpret_cast<const bf16x8*>((const char*)Ks + KSWZ(r32, cb));
;     bf16x8 b1 = *reinterpret_cast<const bf16x8*>((const char*)Ks + KSWZ(32 + r32, cb));
;     p0 = __builtin_amdgcn_mfma_f32_32x32x16_bf16(b0, qr[d0], p0, 0, 0, 0);
;     p1 = __builtin_amdgcn_mfma_f32_32x32x16_bf16(b1, qr[d0], p1, 0, 0, 0); }
;   if (k0 + KVBLK > L) {
; #pragma unroll
;     for (int r = 0; r < 16; ++r) { const int key = k0 + crow(r, hi);
;       if (key >= L) p0[r] = -1e30f;
;       if (key + 32 >= L) p1[r] = -1e30f; }
;   }
; }
; __device__ __forceinline__ int v_st(int k, int c) { const int kk = (k & ~0xC) | ((k & 4) << 1) | ((k & 8) >> 1); return ((kk >> 3) * 4 + (c >> 5)) * 512 + ((kk & 7) * 32 + (c & 31)) * 2; }
; __device__ __forceinline__ int v_rd_base(int lane) { return ((lane & 3) << 3) | (((lane >> 2) & 3) << 6) | (((lane >> 4) & 1) << 5) | (((lane >> 5) & 1) << 8); }
; template <int OFF> __device__ __forceinline__ s16x4 tr_read(int vb) {
;   s16x4 r; asm volatile("ds_read_b64_tr_b16 %0, %1 offset:%2" : "=&v"(r) : "v"(vb), "i"(OFF) : "memory"); return r;
; }
; template <int D0> __device__ __forceinline__ void pv_one(f32x16& od, int vb, bf16x8 pa0, bf16x8 pa1, bf16x8 pa2, bf16x8 pa3) {
;   const s16x4 l0 = tr_read<v_rd_off(D0, 0, 0)>(vb), h0 = tr_read<v_rd_off(D0, 0, 1)>(vb), l1 = tr_read<v_rd_off(D0, 1, 0)>(vb), h1 = tr_read<v_rd_off(D0, 1, 1)>(vb);
;   const s16x4 l2 = tr_read<v_rd_off(D0, 2, 0)>(vb), h2 = tr_read<v_rd_off(D0, 2, 1)>(vb), l3 = tr_read<v_rd_off(D0, 3, 0)>(vb), h3 = tr_read<v_rd_off(D0, 3, 1)>(vb);
; template <int DQK, bool FIX>
; __device__ __forceinline__ void attn_item(const bf16* Qb, const bf16* __restrict__ Kh, const bf16* __restrict__ Vh,
;                                           u16* Ob, int q0, int L, int NT, char* lds, float mC) {
;     ...
;     if (act) { SBAR(); qkt<DQK>(pB0, pB1, (bf16*)((char*)K_lds + SHM_K), qr, r32, hi, j * KVBLK, L);
;       finishSM(pA0, pA1, alA, l_reg, pa0, pa1, pa2, pa3); SBAR(); }
;     SLOAD(SO, (j + 2) * KVBLK); SBAR();
;     if (act) { pv_d0(o, vb0, pa0, pa1, pa2, pa3); partialSM<DQK, FIX>(pB0, pB1, m_reg, mnB, alB, mC); }
.LBB0_832:
	s_and_saveexec_b64 s[2:3], s[8:9]
	s_cbranch_execz .LBB0_838
	s_add_i32 s6, s78, 64
	s_cmp_le_u32 s6, s79
	s_cbranch_scc0 .Lslow64a
	s_and_b64 vcc, exec, s[10:11]
	s_cbranch_vccz .Lslow64a
	ds_read_b128 v[222:225], v167 offset:49152
	ds_read_b128 v[226:229], v168 offset:49152
	ds_read_b128 v[230:233], v167 offset:57344
	ds_read_b128 v[234:237], v168 offset:57344
	ds_read_b128 v[238:241], v169 offset:49152
	ds_read_b128 v[242:245], v169 offset:57344
	ds_read_b128 v[246:249], v171 offset:49152
	ds_read_b128 v[250:253], v171 offset:57344
	v_cvt_pk_bf16_f32 v130, v50, v51
	v_cvt_pk_bf16_f32 v131, v52, v53
	v_cvt_pk_bf16_f32 v132, v54, v55
	v_cvt_pk_bf16_f32 v133, v56, v57
	v_cvt_pk_bf16_f32 v134, v58, v59
	v_cvt_pk_bf16_f32 v135, v60, v61
	v_cvt_pk_bf16_f32 v136, v62, v63
	v_cvt_pk_bf16_f32 v137, v64, v65
	s_waitcnt lgkmcnt(7)
	v_mfma_f32_32x32x16_bf16 v[66:81], v[222:225], v[98:101], 0
	ds_read_b64_tr_b16 v[186:187], v166 offset:0
	ds_read_b64_tr_b16 v[188:189], v166 offset:2048
	ds_read_b64_tr_b16 v[190:191], v166 offset:4096
	ds_read_b64_tr_b16 v[192:193], v166 offset:6144
	v_exp_f32_e32 v34, v34
	v_exp_f32_e32 v35, v35
	v_add_f32_e32 v208, 0, v50
	v_add_f32_e32 v208, v51, v208
	s_waitcnt lgkmcnt(8)
	v_mfma_f32_32x32x16_bf16 v[66:81], v[226:229], v[102:105], v[66:81]
	ds_read_b64_tr_b16 v[194:195], v166 offset:8192
	ds_read_b64_tr_b16 v[196:197], v166 offset:10240
	ds_read_b64_tr_b16 v[198:199], v166 offset:12288
	ds_read_b64_tr_b16 v[200:201], v166 offset:14336
	v_exp_f32_e32 v36, v36
	v_exp_f32_e32 v37, v37
	v_exp_f32_e32 v38, v38
	v_add_f32_e32 v208, v52, v208
	v_mfma_f32_32x32x16_bf16 v[82:97], v[230:233], v[98:101], 0
	v_exp_f32_e32 v39, v39
	v_exp_f32_e32 v40, v40
	v_add_f32_e32 v208, v53, v208
	v_add_f32_e32 v208, v54, v208
	v_mfma_f32_32x32x16_bf16 v[82:97], v[234:237], v[102:105], v[82:97]
	v_exp_f32_e32 v41, v41
	v_exp_f32_e32 v42, v42
	v_exp_f32_e32 v43, v43
	v_add_f32_e32 v208, v55, v208
	s_waitcnt lgkmcnt(8)
	v_mfma_f32_32x32x16_bf16 v[66:81], v[238:241], v[106:109], v[66:81]
	v_exp_f32_e32 v44, v44
	v_exp_f32_e32 v45, v45
	v_add_f32_e32 v208, v56, v208
	v_add_f32_e32 v208, v57, v208
	v_mfma_f32_32x32x16_bf16 v[82:97], v[242:245], v[106:109], v[82:97]
	ds_read_b64_tr_b16 v[222:223], v166 offset:512
	ds_read_b64_tr_b16 v[224:225], v166 offset:2560
	ds_read_b64_tr_b16 v[226:227], v166 offset:4608
	ds_read_b64_tr_b16 v[228:229], v166 offset:6656
	v_exp_f32_e32 v46, v46
	v_exp_f32_e32 v47, v47
	v_exp_f32_e32 v48, v48
	v_add_f32_e32 v208, v58, v208
	v_mfma_f32_32x32x16_bf16 v[66:81], v[246:249], v[110:113], v[66:81]
	v_exp_f32_e32 v49, v49
	v_cvt_pk_bf16_f32 v138, v34, v35
	v_cvt_pk_bf16_f32 v139, v36, v37
	v_cvt_pk_bf16_f32 v140, v38, v39
	v_add_f32_e32 v208, v59, v208
	v_mfma_f32_32x32x16_bf16 v[82:97], v[250:253], v[110:113], v[82:97]
	ds_read_b64_tr_b16 v[230:231], v166 offset:8704
	ds_read_b64_tr_b16 v[232:233], v166 offset:10752
	ds_read_b64_tr_b16 v[234:235], v166 offset:12800
	s_waitcnt lgkmcnt(14)
	ds_read_b64_tr_b16 v[236:237], v166 offset:14848
	v_cvt_pk_bf16_f32 v141, v40, v41
	v_cvt_pk_bf16_f32 v142, v42, v43
	v_cvt_pk_bf16_f32 v143, v44, v45
	v_cvt_pk_bf16_f32 v144, v46, v47
	v_cvt_pk_bf16_f32 v145, v48, v49
	v_add_f32_e32 v208, v60, v208
	v_add_f32_e32 v208, v61, v208
	s_or_b64 exec, exec, s[2:3]
	global_load_dwordx4 v[122:125], v211, s[80:81] offset:2048
	global_load_dwordx4 v[126:129], v210, s[74:75]
	s_and_saveexec_b64 s[2:3], s[8:9]
	s_waitcnt lgkmcnt(0)
	v_mfma_f32_32x32x16_bf16 v[2:17], v[130:133], v[186:189], v[2:17]
	v_add_f32_e32 v208, v62, v208
	v_add_f32_e32 v208, v63, v208
	v_exp_f32_e32 v66, v66
	v_exp_f32_e32 v67, v67
	v_mfma_f32_32x32x16_bf16 v[2:17], v[134:137], v[190:193], v[2:17]
	v_add_f32_e32 v208, v64, v208
	v_add_f32_e32 v208, v65, v208
	v_add_f32_e32 v208, v34, v208
	v_exp_f32_e32 v68, v68
	v_exp_f32_e32 v69, v69
	v_mfma_f32_32x32x16_bf16 v[2:17], v[138:141], v[194:197], v[2:17]
	v_add_f32_e32 v208, v35, v208
	v_add_f32_e32 v208, v36, v208
	v_add_f32_e32 v208, v37, v208
	v_exp_f32_e32 v70, v70
	v_exp_f32_e32 v71, v71
	v_mfma_f32_32x32x16_bf16 v[2:17], v[142:145], v[198:201], v[2:17]
	v_add_f32_e32 v208, v38, v208
	v_add_f32_e32 v208, v39, v208
	v_exp_f32_e32 v72, v72
	v_exp_f32_e32 v73, v73
	v_mfma_f32_32x32x16_bf16 v[18:33], v[130:133], v[222:225], v[18:33]
	v_add_f32_e32 v208, v40, v208
	v_add_f32_e32 v208, v41, v208
	v_exp_f32_e32 v74, v74
	v_exp_f32_e32 v75, v75
	v_mfma_f32_32x32x16_bf16 v[18:33], v[134:137], v[226:229], v[18:33]
	v_add_f32_e32 v208, v42, v208
	v_add_f32_e32 v208, v43, v208
	v_add_f32_e32 v208, v44, v208
	v_exp_f32_e32 v76, v76
	v_exp_f32_e32 v77, v77
	v_mfma_f32_32x32x16_bf16 v[18:33], v[138:141], v[230:233], v[18:33]
	v_add_f32_e32 v208, v45, v208
	v_add_f32_e32 v208, v46, v208
	v_add_f32_e32 v208, v47, v208
	v_exp_f32_e32 v78, v78
	v_exp_f32_e32 v79, v79
	v_mfma_f32_32x32x16_bf16 v[18:33], v[142:145], v[234:237], v[18:33]
	v_add_f32_e32 v208, v48, v208
	v_add_f32_e32 v208, v49, v208
	v_exp_f32_e32 v80, v80
	v_exp_f32_e32 v81, v81
	v_add_f32_e32 v202, v202, v208
	s_branch .LBB0_842

; #define SBAR() __builtin_amdgcn_sched_barrier(0)
; template <int DQK>
; __device__ __forceinline__ void qkt(f32x16& p0, f32x16& p1, const bf16* Ks, const bf16x8* qr, int r32, int hi, int k0, int L) {
;   p0 = f32x16{}; p1 = f32x16{};
; #pragma unroll
;   for (int d0 = 0; d0 < DQK / 16; ++d0) { int cb = (d0 * 16 + hi * 8) * 2;
;     bf16x8 b0 = *reinterpret_cast<const bf16x8*>((const char*)Ks + KSWZ(r32, cb));
;     bf16x8 b1 = *reinterpret_cast<const bf16x8*>((const char*)Ks + KSWZ(32 + r32, cb));
;     p0 = __builtin_amdgcn_mfma_f32_32x32x16_bf16(b0, qr[d0], p0, 0, 0, 0);
;     p1 = __builtin_amdgcn_mfma_f32_32x32x16_bf16(b1, qr[d0], p1, 0, 0, 0); }
;   if (k0 + KVBLK > L) {
; #pragma unroll
;     for (int r = 0; r < 16; ++r) { const int key = k0 + crow(r, hi);
;       if (key >= L) p0[r] = -1e30f;
;       if (key + 32 >= L) p1[r] = -1e30f; }
;   }
; }
; __device__ __forceinline__ int v_st(int k, int c) { const int kk = (k & ~0xC) | ((k & 4) << 1) | ((k & 8) >> 1); return ((kk >> 3) * 4 + (c >> 5)) * 512 + ((kk & 7) * 32 + (c & 31)) * 2; }
; __device__ __forceinline__ int v_rd_base(int lane) { return ((lane & 3) << 3) | (((lane >> 2) & 3) << 6) | (((lane >> 4) & 1) << 5) | (((lane >> 5) & 1) << 8); }
; template <int OFF> __device__ __forceinline__ s16x4 tr_read(int vb) {
;   s16x4 r; asm volatile("ds_read_b64_tr_b16 %0, %1 offset:%2" : "=&v"(r) : "v"(vb), "i"(OFF) : "memory"); return r;
; }
; template <int D0> __device__ __forceinline__ void pv_one(f32x16& od, int vb, bf16x8 pa0, bf16x8 pa1, bf16x8 pa2, bf16x8 pa3) {
;   const s16x4 l0 = tr_read<v_rd_off(D0, 0, 0)>(vb), h0 = tr_read<v_rd_off(D0, 0, 1)>(vb), l1 = tr_read<v_rd_off(D0, 1, 0)>(vb), h1 = tr_read<v_rd_off(D0, 1, 1)>(vb);
; template <int DQK, bool FIX>
; __device__ __forceinline__ void attn_item(const bf16* Qb, const bf16* __restrict__ Kh, const bf16* __restrict__ Vh,
;                                           u16* Ob, int q0, int L, int NT, char* lds, float mC) {
;     ...
;     __syncthreads(); SWAIT(); SWRITE(0, SE);
;     if (act) { RESC(alB); } __syncthreads();
;     if (act) { SBAR(); qkt<DQK>(pA0, pA1, K_lds, qr, r32, hi, (j + 1) * KVBLK, L);
;       finishSM(pB0, pB1, alB, l_reg, pa0, pa1, pa2, pa3); SBAR(); }
;     if (j + 3 < NT) SLOAD(SE, (j + 3) * KVBLK); SBAR();
;     if (act) { pv_d0(o, vb0 + (int)SHM_V, pa0, pa1, pa2, pa3); partialSM<DQK, FIX>(pA0, pA1, m_reg, mnA, alA, mC); }
.LBB0_842:
	s_or_b64 exec, exec, s[2:3]
	s_waitcnt lgkmcnt(0)
	s_barrier
	s_waitcnt vmcnt(2)
	s_waitcnt vmcnt(2)
	ds_write_b128 v160, v[114:117]
	ds_write_b128 v161, v[118:121] offset:49152
	s_and_saveexec_b64 s[2:3], s[8:9]
	s_cbranch_execz .LBB0_848
	s_add_i32 s6, s78, 0x80
	s_cmp_le_u32 s6, s79
	s_cbranch_scc0 .Lslow64b
	s_and_b64 vcc, exec, s[10:11]
	s_cbranch_vccz .Lslow64b
	ds_read_b128 v[222:225], v167 offset:32768
	ds_read_b128 v[226:229], v168 offset:32768
	ds_read_b128 v[230:233], v167 offset:40960
	ds_read_b128 v[234:237], v168 offset:40960
	ds_read_b128 v[238:241], v169 offset:32768
	ds_read_b128 v[242:245], v169 offset:40960
	ds_read_b128 v[246:249], v171 offset:32768
	ds_read_b128 v[250:253], v171 offset:40960
	v_cvt_pk_bf16_f32 v130, v66, v67
	v_cvt_pk_bf16_f32 v131, v68, v69
	v_cvt_pk_bf16_f32 v132, v70, v71
	v_cvt_pk_bf16_f32 v133, v72, v73
	v_cvt_pk_bf16_f32 v134, v74, v75
	v_cvt_pk_bf16_f32 v135, v76, v77
	v_cvt_pk_bf16_f32 v136, v78, v79
	v_cvt_pk_bf16_f32 v137, v80, v81
	s_waitcnt lgkmcnt(7)
	v_mfma_f32_32x32x16_bf16 v[50:65], v[222:225], v[98:101], 0
	ds_read_b64_tr_b16 v[186:187], v170 offset:0
	ds_read_b64_tr_b16 v[188:189], v170 offset:2048
	ds_read_b64_tr_b16 v[190:191], v170 offset:4096
	ds_read_b64_tr_b16 v[192:193], v170 offset:6144
	v_exp_f32_e32 v82, v82
	v_exp_f32_e32 v83, v83
	v_add_f32_e32 v208, 0, v66
	v_add_f32_e32 v208, v67, v208
	s_waitcnt lgkmcnt(8)
	v_mfma_f32_32x32x16_bf16 v[50:65], v[226:229], v[102:105], v[50:65]
	ds_read_b64_tr_b16 v[194:195], v170 offset:8192
	ds_read_b64_tr_b16 v[196:197], v170 offset:10240
	ds_read_b64_tr_b16 v[198:199], v170 offset:12288
	ds_read_b64_tr_b16 v[200:201], v170 offset:14336
	v_exp_f32_e32 v84, v84
	v_exp_f32_e32 v85, v85
	v_exp_f32_e32 v86, v86
	v_add_f32_e32 v208, v68, v208
	v_mfma_f32_32x32x16_bf16 v[34:49], v[230:233], v[98:101], 0
	v_exp_f32_e32 v87, v87
	v_exp_f32_e32 v88, v88
	v_add_f32_e32 v208, v69, v208
	v_add_f32_e32 v208, v70, v208
	v_mfma_f32_32x32x16_bf16 v[34:49], v[234:237], v[102:105], v[34:49]
	v_exp_f32_e32 v89, v89
	v_exp_f32_e32 v90, v90
	v_exp_f32_e32 v91, v91
	v_add_f32_e32 v208, v71, v208
	s_waitcnt lgkmcnt(8)
	v_mfma_f32_32x32x16_bf16 v[50:65], v[238:241], v[106:109], v[50:65]
	v_exp_f32_e32 v92, v92
	v_exp_f32_e32 v93, v93
	v_add_f32_e32 v208, v72, v208
	v_add_f32_e32 v208, v73, v208
	v_mfma_f32_32x32x16_bf16 v[34:49], v[242:245], v[106:109], v[34:49]
	ds_read_b64_tr_b16 v[222:223], v170 offset:512
	ds_read_b64_tr_b16 v[224:225], v170 offset:2560
	ds_read_b64_tr_b16 v[226:227], v170 offset:4608
	ds_read_b64_tr_b16 v[228:229], v170 offset:6656
	v_exp_f32_e32 v94, v94
	v_exp_f32_e32 v95, v95
	v_exp_f32_e32 v96, v96
	v_add_f32_e32 v208, v74, v208
	v_mfma_f32_32x32x16_bf16 v[50:65], v[246:249], v[110:113], v[50:65]
	v_exp_f32_e32 v97, v97
	v_cvt_pk_bf16_f32 v138, v82, v83
	v_cvt_pk_bf16_f32 v139, v84, v85
	v_cvt_pk_bf16_f32 v140, v86, v87
	v_add_f32_e32 v208, v75, v208
	v_mfma_f32_32x32x16_bf16 v[34:49], v[250:253], v[110:113], v[34:49]
	ds_read_b64_tr_b16 v[230:231], v170 offset:8704
	ds_read_b64_tr_b16 v[232:233], v170 offset:10752
	ds_read_b64_tr_b16 v[234:235], v170 offset:12800
	s_waitcnt lgkmcnt(14)
	ds_read_b64_tr_b16 v[236:237], v170 offset:14848
	v_cvt_pk_bf16_f32 v141, v88, v89
	v_cvt_pk_bf16_f32 v142, v90, v91
	v_cvt_pk_bf16_f32 v143, v92, v93
	v_cvt_pk_bf16_f32 v144, v94, v95
	v_cvt_pk_bf16_f32 v145, v96, v97
	v_add_f32_e32 v208, v76, v208
	v_add_f32_e32 v208, v77, v208
	s_or_b64 exec, exec, s[2:3]
	s_cmp_ge_u32 s73, s97
	s_cselect_b64 s[2:3], -1, 0
	s_and_b64 vcc, exec, s[2:3]
	s_cbranch_vccnz .Lfast64b_nl
	global_load_dwordx4 v[114:117], v211, s[84:85] offset:2048
	global_load_dwordx4 v[118:121], v210, s[76:77]
.Lfast64b_nl:
	s_and_saveexec_b64 s[6:7], s[8:9]
	s_waitcnt lgkmcnt(0)
	v_mfma_f32_32x32x16_bf16 v[2:17], v[130:133], v[186:189], v[2:17]
	v_add_f32_e32 v208, v78, v208
	v_add_f32_e32 v208, v79, v208
	v_exp_f32_e32 v50, v50
	v_exp_f32_e32 v51, v51
	v_mfma_f32_32x32x16_bf16 v[2:17], v[134:137], v[190:193], v[2:17]
	v_add_f32_e32 v208, v80, v208
	v_add_f32_e32 v208, v81, v208
	v_add_f32_e32 v208, v82, v208
	v_exp_f32_e32 v52, v52
	v_exp_f32_e32 v53, v53
	v_mfma_f32_32x32x16_bf16 v[2:17], v[138:141], v[194:197], v[2:17]
	v_add_f32_e32 v208, v83, v208
	v_add_f32_e32 v208, v84, v208
	v_add_f32_e32 v208, v85, v208
	v_exp_f32_e32 v54, v54
	v_exp_f32_e32 v55, v55
	v_mfma_f32_32x32x16_bf16 v[2:17], v[142:145], v[198:201], v[2:17]
	v_add_f32_e32 v208, v86, v208
	v_add_f32_e32 v208, v87, v208
	v_exp_f32_e32 v56, v56
	v_exp_f32_e32 v57, v57
	v_mfma_f32_32x32x16_bf16 v[18:33], v[130:133], v[222:225], v[18:33]
	v_add_f32_e32 v208, v88, v208
	v_add_f32_e32 v208, v89, v208
	v_exp_f32_e32 v58, v58
	v_exp_f32_e32 v59, v59
	v_mfma_f32_32x32x16_bf16 v[18:33], v[134:137], v[226:229], v[18:33]
	v_add_f32_e32 v208, v90, v208
	v_add_f32_e32 v208, v91, v208
	v_add_f32_e32 v208, v92, v208
	v_exp_f32_e32 v60, v60
	v_exp_f32_e32 v61, v61
	v_mfma_f32_32x32x16_bf16 v[18:33], v[138:141], v[230:233], v[18:33]
	v_add_f32_e32 v208, v93, v208
	v_add_f32_e32 v208, v94, v208
	v_add_f32_e32 v208, v95, v208
	v_exp_f32_e32 v62, v62
	v_exp_f32_e32 v63, v63
	v_mfma_f32_32x32x16_bf16 v[18:33], v[142:145], v[234:237], v[18:33]
	v_add_f32_e32 v208, v96, v208
	v_add_f32_e32 v208, v97, v208
	v_exp_f32_e32 v64, v64
	v_exp_f32_e32 v65, v65
	v_add_f32_e32 v202, v202, v208
	s_branch .LBB0_831

; template <int DQK>
; __device__ __forceinline__ void qkt(f32x16& p0, f32x16& p1, const bf16* Ks, const bf16x8* qr, int r32, int hi, int k0, int L) {
;   p0 = f32x16{}; p1 = f32x16{};
; #pragma unroll
;   for (int d0 = 0; d0 < DQK / 16; ++d0) { int cb = (d0 * 16 + hi * 8) * 2;
;     bf16x8 b0 = *reinterpret_cast<const bf16x8*>((const char*)Ks + KSWZ(r32, cb));
;     bf16x8 b1 = *reinterpret_cast<const bf16x8*>((const char*)Ks + KSWZ(32 + r32, cb));
;     p0 = __builtin_amdgcn_mfma_f32_32x32x16_bf16(b0, qr[d0], p0, 0, 0, 0);
;     p1 = __builtin_amdgcn_mfma_f32_32x32x16_bf16(b1, qr[d0], p1, 0, 0, 0); }
;   if (k0 + KVBLK > L) {
; #pragma unroll
;     for (int r = 0; r < 16; ++r) { const int key = k0 + crow(r, hi);
;       if (key >= L) p0[r] = -1e30f;
;       if (key + 32 >= L) p1[r] = -1e30f; }
;   }
; }
; __device__ __forceinline__ int v_st(int k, int c) { const int kk = (k & ~0xC) | ((k & 4) << 1) | ((k & 8) >> 1); return ((kk >> 3) * 4 + (c >> 5)) * 512 + ((kk & 7) * 32 + (c & 31)) * 2; }
; __device__ __forceinline__ int v_rd_base(int lane) { return ((lane & 3) << 3) | (((lane >> 2) & 3) << 6) | (((lane >> 4) & 1) << 5) | (((lane >> 5) & 1) << 8); }
; template <int OFF> __device__ __forceinline__ s16x4 tr_read(int vb) {
;   s16x4 r; asm volatile("ds_read_b64_tr_b16 %0, %1 offset:%2" : "=&v"(r) : "v"(vb), "i"(OFF) : "memory"); return r;
; }
; template <int D0> __device__ __forceinline__ void pv_one(f32x16& od, int vb, bf16x8 pa0, bf16x8 pa1, bf16x8 pa2, bf16x8 pa3) {
;   const s16x4 l0 = tr_read<v_rd_off(D0, 0, 0)>(vb), h0 = tr_read<v_rd_off(D0, 0, 1)>(vb), l1 = tr_read<v_rd_off(D0, 1, 0)>(vb), h1 = tr_read<v_rd_off(D0, 1, 1)>(vb);
;   const s16x4 l2 = tr_read<v_rd_off(D0, 2, 0)>(vb), h2 = tr_read<v_rd_off(D0, 2, 1)>(vb), l3 = tr_read<v_rd_off(D0, 3, 0)>(vb), h3 = tr_read<v_rd_off(D0, 3, 1)>(vb);
; template <int DQK, bool FIX>
; __device__ __forceinline__ void attn_item(const bf16* Qb, const bf16* __restrict__ Kh, const bf16* __restrict__ Vh,
;                                           u16* Ob, int q0, int L, int NT, char* lds, float mC) {
;     ...
;     if (act) { SBAR(); qkt<DQK>(pB0, pB1, (bf16*)((char*)K_lds + SHM_K), qr, r32, hi, j * KVBLK, L);
;       finishSM(pA0, pA1, alA, l_reg, pa0, pa1, pa2, pa3); SBAR(); }
;     SLOAD(SO, (j + 2) * KVBLK); SBAR();
;     if (act) { pv_d0(o, vb0, pa0, pa1, pa2, pa3); partialSM<DQK, FIX>(pB0, pB1, m_reg, mnB, alB, mC); }
.LBB0_883:
	s_and_saveexec_b64 s[2:3], s[10:11]
	s_cbranch_execz .LBB0_889
	s_add_i32 s14, s4, 64
	s_cmp_le_u32 s14, s5
	s_cbranch_scc0 .Lslow96a
	s_and_b64 vcc, exec, s[12:13]
	s_cbranch_vccz .Lslow96a
	ds_read_b128 v[222:225], v200 offset:49152
	ds_read_b128 v[226:229], v200 offset:57344
	ds_read_b128 v[230:233], v201 offset:49152
	ds_read_b128 v[234:237], v201 offset:57344
	ds_read_b128 v[238:241], v202 offset:49152
	ds_read_b128 v[242:245], v202 offset:57344
	ds_read_b128 v[246:249], v203 offset:49152
	ds_read_b128 v[250:253], v203 offset:57344
	v_cvt_pk_bf16_f32 v10, v64, v65
	v_cvt_pk_bf16_f32 v11, v66, v67
	v_cvt_pk_bf16_f32 v12, v68, v69
	v_cvt_pk_bf16_f32 v13, v70, v71
	v_cvt_pk_bf16_f32 v152, v72, v73
	v_cvt_pk_bf16_f32 v153, v74, v75
	v_cvt_pk_bf16_f32 v154, v76, v77
	v_cvt_pk_bf16_f32 v155, v78, v79
	s_waitcnt lgkmcnt(7)
	v_mfma_f32_32x32x16_bf16 v[80:95], v[222:225], v[112:115], 0
	ds_read_b128 v[222:225], v204 offset:49152
	ds_read_b64_tr_b16 v[206:207], v197 offset:0
	ds_read_b64_tr_b16 v[208:209], v197 offset:2048
	ds_read_b64_tr_b16 v[210:211], v197 offset:4096
	ds_read_b64_tr_b16 v[212:213], v197 offset:6144
	v_exp_f32_e32 v48, v48
	v_exp_f32_e32 v49, v49
	v_add_f32_e32 v0, 0, v64
	s_waitcnt lgkmcnt(9)
	v_mfma_f32_32x32x16_bf16 v[96:111], v[226:229], v[112:115], 0
	ds_read_b128 v[226:229], v204 offset:57344
	ds_read_b64_tr_b16 v[214:215], v197 offset:8192
	ds_read_b64_tr_b16 v[216:217], v197 offset:10240
	ds_read_b64_tr_b16 v[218:219], v197 offset:12288
	ds_read_b64_tr_b16 v[220:221], v197 offset:14336
	v_exp_f32_e32 v50, v50
	v_exp_f32_e32 v51, v51
	v_add_f32_e32 v0, v65, v0
	v_mfma_f32_32x32x16_bf16 v[80:95], v[230:233], v[116:119], v[80:95]
	ds_read_b128 v[230:233], v205 offset:49152
	v_exp_f32_e32 v52, v52
	v_exp_f32_e32 v53, v53
	v_add_f32_e32 v0, v66, v0
	v_mfma_f32_32x32x16_bf16 v[96:111], v[234:237], v[116:119], v[96:111]
	s_waitcnt lgkmcnt(14)
	ds_read_b128 v[234:237], v205 offset:57344
	v_exp_f32_e32 v54, v54
	v_exp_f32_e32 v55, v55
	v_add_f32_e32 v0, v67, v0
	s_waitcnt lgkmcnt(12)
	v_mfma_f32_32x32x16_bf16 v[80:95], v[238:241], v[120:123], v[80:95]
	v_exp_f32_e32 v56, v56
	v_exp_f32_e32 v57, v57
	v_add_f32_e32 v0, v68, v0
	v_mfma_f32_32x32x16_bf16 v[96:111], v[242:245], v[120:123], v[96:111]
	v_exp_f32_e32 v58, v58
	v_exp_f32_e32 v59, v59
	v_add_f32_e32 v0, v69, v0
	v_mfma_f32_32x32x16_bf16 v[80:95], v[246:249], v[124:127], v[80:95]
	v_exp_f32_e32 v60, v60
	v_exp_f32_e32 v61, v61
	v_add_f32_e32 v0, v70, v0
	v_mfma_f32_32x32x16_bf16 v[96:111], v[250:253], v[124:127], v[96:111]
	v_exp_f32_e32 v62, v62
	v_exp_f32_e32 v63, v63
	v_add_f32_e32 v0, v71, v0
	s_waitcnt lgkmcnt(0)
	v_mfma_f32_32x32x16_bf16 v[80:95], v[222:225], v[128:131], v[80:95]
	ds_read_b64_tr_b16 v[238:239], v197 offset:512
	ds_read_b64_tr_b16 v[240:241], v197 offset:2560
	ds_read_b64_tr_b16 v[242:243], v197 offset:4608
	ds_read_b64_tr_b16 v[244:245], v197 offset:6656
	v_cvt_pk_bf16_f32 v156, v48, v49
	v_cvt_pk_bf16_f32 v157, v50, v51
	v_cvt_pk_bf16_f32 v158, v52, v53
	v_cvt_pk_bf16_f32 v159, v54, v55
	v_add_f32_e32 v0, v72, v0
	v_add_f32_e32 v0, v73, v0
	v_mfma_f32_32x32x16_bf16 v[96:111], v[226:229], v[128:131], v[96:111]
	v_cvt_pk_bf16_f32 v160, v56, v57
	v_cvt_pk_bf16_f32 v161, v58, v59
	v_cvt_pk_bf16_f32 v162, v60, v61
	v_cvt_pk_bf16_f32 v163, v62, v63
	v_add_f32_e32 v0, v74, v0
	v_add_f32_e32 v0, v75, v0
	v_mfma_f32_32x32x16_bf16 v[80:95], v[230:233], v[132:135], v[80:95]
	ds_read_b64_tr_b16 v[246:247], v197 offset:8704
	ds_read_b64_tr_b16 v[248:249], v197 offset:10752
	ds_read_b64_tr_b16 v[250:251], v197 offset:12800
	ds_read_b64_tr_b16 v[252:253], v197 offset:14848
	v_add_f32_e32 v0, v76, v0
	v_add_f32_e32 v0, v77, v0
	v_add_f32_e32 v0, v78, v0
	v_add_f32_e32 v0, v79, v0
	v_add_f32_e32 v0, v48, v0
	v_mfma_f32_32x32x16_bf16 v[96:111], v[234:237], v[132:135], v[96:111]
	v_add_f32_e32 v0, v49, v0
	v_add_f32_e32 v0, v50, v0
	v_add_f32_e32 v0, v51, v0
	v_add_f32_e32 v0, v52, v0
	v_add_f32_e32 v0, v53, v0
	s_or_b64 exec, exec, s[2:3]
	global_load_dwordx4 v[2:5], v14, s[80:81]
	global_load_dwordx4 v[6:9], v15, s[74:75]
	s_and_saveexec_b64 s[2:3], s[8:9]
	s_cbranch_execz .Lfast96a_k2
	global_load_dwordx4 v[140:143], v188, s[74:75]
.Lfast96a_k2:
	s_or_b64 exec, exec, s[2:3]
	s_and_saveexec_b64 s[2:3], s[10:11]
	s_waitcnt lgkmcnt(0)
	v_mfma_f32_32x32x16_bf16 v[32:47], v[10:13], v[206:209], v[32:47]
	v_add_f32_e32 v0, v54, v0
	v_exp_f32_e32 v80, v80
	v_exp_f32_e32 v81, v81
	v_mfma_f32_32x32x16_bf16 v[32:47], v[152:155], v[210:213], v[32:47]
	v_add_f32_e32 v0, v55, v0
	v_exp_f32_e32 v82, v82
	v_exp_f32_e32 v83, v83
	v_mfma_f32_32x32x16_bf16 v[32:47], v[156:159], v[214:217], v[32:47]
	v_add_f32_e32 v0, v56, v0
	v_add_f32_e32 v0, v57, v0
	v_exp_f32_e32 v84, v84
	v_exp_f32_e32 v85, v85
	v_mfma_f32_32x32x16_bf16 v[32:47], v[160:163], v[218:221], v[32:47]
	v_add_f32_e32 v0, v58, v0
	v_exp_f32_e32 v86, v86
	v_exp_f32_e32 v87, v87
	v_mfma_f32_32x32x16_bf16 v[16:31], v[10:13], v[238:241], v[16:31]
	v_add_f32_e32 v0, v59, v0
	v_exp_f32_e32 v88, v88
	v_exp_f32_e32 v89, v89
	v_mfma_f32_32x32x16_bf16 v[16:31], v[152:155], v[242:245], v[16:31]
	v_add_f32_e32 v0, v60, v0
	v_add_f32_e32 v0, v61, v0
	v_exp_f32_e32 v90, v90
	v_exp_f32_e32 v91, v91
	v_mfma_f32_32x32x16_bf16 v[16:31], v[156:159], v[246:249], v[16:31]
	v_add_f32_e32 v0, v62, v0
	v_exp_f32_e32 v92, v92
	v_exp_f32_e32 v93, v93
	v_mfma_f32_32x32x16_bf16 v[16:31], v[160:163], v[250:253], v[16:31]
	v_add_f32_e32 v0, v63, v0
	v_exp_f32_e32 v94, v94
	v_exp_f32_e32 v95, v95
	v_add_f32_e32 v186, v186, v0
	s_branch .LBB0_895

; #define SBAR() __builtin_amdgcn_sched_barrier(0)
; template <int DQK>
; __device__ __forceinline__ void qkt(f32x16& p0, f32x16& p1, const bf16* Ks, const bf16x8* qr, int r32, int hi, int k0, int L) {
;   p0 = f32x16{}; p1 = f32x16{};
; #pragma unroll
;   for (int d0 = 0; d0 < DQK / 16; ++d0) { int cb = (d0 * 16 + hi * 8) * 2;
;     bf16x8 b0 = *reinterpret_cast<const bf16x8*>((const char*)Ks + KSWZ(r32, cb));
;     bf16x8 b1 = *reinterpret_cast<const bf16x8*>((const char*)Ks + KSWZ(32 + r32, cb));
;     p0 = __builtin_amdgcn_mfma_f32_32x32x16_bf16(b0, qr[d0], p0, 0, 0, 0);
;     p1 = __builtin_amdgcn_mfma_f32_32x32x16_bf16(b1, qr[d0], p1, 0, 0, 0); }
;   if (k0 + KVBLK > L) {
; #pragma unroll
;     for (int r = 0; r < 16; ++r) { const int key = k0 + crow(r, hi);
;       if (key >= L) p0[r] = -1e30f;
;       if (key + 32 >= L) p1[r] = -1e30f; }
;   }
; }
; __device__ __forceinline__ int v_st(int k, int c) { const int kk = (k & ~0xC) | ((k & 4) << 1) | ((k & 8) >> 1); return ((kk >> 3) * 4 + (c >> 5)) * 512 + ((kk & 7) * 32 + (c & 31)) * 2; }
; __device__ __forceinline__ int v_rd_base(int lane) { return ((lane & 3) << 3) | (((lane >> 2) & 3) << 6) | (((lane >> 4) & 1) << 5) | (((lane >> 5) & 1) << 8); }
; template <int OFF> __device__ __forceinline__ s16x4 tr_read(int vb) {
;   s16x4 r; asm volatile("ds_read_b64_tr_b16 %0, %1 offset:%2" : "=&v"(r) : "v"(vb), "i"(OFF) : "memory"); return r;
; }
; template <int D0> __device__ __forceinline__ void pv_one(f32x16& od, int vb, bf16x8 pa0, bf16x8 pa1, bf16x8 pa2, bf16x8 pa3) {
;   const s16x4 l0 = tr_read<v_rd_off(D0, 0, 0)>(vb), h0 = tr_read<v_rd_off(D0, 0, 1)>(vb), l1 = tr_read<v_rd_off(D0, 1, 0)>(vb), h1 = tr_read<v_rd_off(D0, 1, 1)>(vb);
; template <int DQK, bool FIX>
; __device__ __forceinline__ void attn_item(const bf16* Qb, const bf16* __restrict__ Kh, const bf16* __restrict__ Vh,
;                                           u16* Ob, int q0, int L, int NT, char* lds, float mC) {
;     ...
;     __syncthreads(); SWAIT(); SWRITE(0, SE);
;     if (act) { RESC(alB); } __syncthreads();
;     if (act) { SBAR(); qkt<DQK>(pA0, pA1, K_lds, qr, r32, hi, (j + 1) * KVBLK, L);
;       finishSM(pB0, pB1, alB, l_reg, pa0, pa1, pa2, pa3); SBAR(); }
;     if (j + 3 < NT) SLOAD(SE, (j + 3) * KVBLK); SBAR();
;     if (act) { pv_d0(o, vb0 + (int)SHM_V, pa0, pa1, pa2, pa3); partialSM<DQK, FIX>(pA0, pA1, m_reg, mnA, alA, mC); }
.LBB0_895:
	s_or_b64 exec, exec, s[2:3]
	s_waitcnt lgkmcnt(0)
	s_barrier
	s_waitcnt vmcnt(2)
	s_waitcnt vmcnt(3)
	ds_write_b128 v193, v[144:147]
	s_waitcnt vmcnt(2)
	ds_write_b128 v194, v[148:151] offset:49152
	s_and_saveexec_b64 s[2:3], s[8:9]
	ds_write_b128 v195, v[136:139] offset:49152
	s_or_b64 exec, exec, s[2:3]
	s_and_saveexec_b64 s[2:3], s[10:11]
	s_cbranch_execz .LBB0_903
	s_add_i32 s14, s4, 0x80
	s_cmp_le_u32 s14, s5
	s_cbranch_scc0 .Lslow96b
	s_and_b64 vcc, exec, s[12:13]
	s_cbranch_vccz .Lslow96b
	ds_read_b128 v[222:225], v200 offset:32768
	ds_read_b128 v[226:229], v200 offset:40960
	ds_read_b128 v[230:233], v201 offset:32768
	ds_read_b128 v[234:237], v201 offset:40960
	ds_read_b128 v[238:241], v202 offset:32768
	ds_read_b128 v[242:245], v202 offset:40960
	ds_read_b128 v[246:249], v203 offset:32768
	ds_read_b128 v[250:253], v203 offset:40960
	v_cvt_pk_bf16_f32 v10, v80, v81
	v_cvt_pk_bf16_f32 v11, v82, v83
	v_cvt_pk_bf16_f32 v12, v84, v85
	v_cvt_pk_bf16_f32 v13, v86, v87
	v_cvt_pk_bf16_f32 v152, v88, v89
	v_cvt_pk_bf16_f32 v153, v90, v91
	v_cvt_pk_bf16_f32 v154, v92, v93
	v_cvt_pk_bf16_f32 v155, v94, v95
	s_waitcnt lgkmcnt(7)
	v_mfma_f32_32x32x16_bf16 v[64:79], v[222:225], v[112:115], 0
	ds_read_b128 v[222:225], v204 offset:32768
	ds_read_b64_tr_b16 v[206:207], v199 offset:0
	ds_read_b64_tr_b16 v[208:209], v199 offset:2048
	ds_read_b64_tr_b16 v[210:211], v199 offset:4096
	ds_read_b64_tr_b16 v[212:213], v199 offset:6144
	v_exp_f32_e32 v96, v96
	v_exp_f32_e32 v97, v97
	v_add_f32_e32 v0, 0, v80
	s_waitcnt lgkmcnt(9)
	v_mfma_f32_32x32x16_bf16 v[48:63], v[226:229], v[112:115], 0
	ds_read_b128 v[226:229], v204 offset:40960
	ds_read_b64_tr_b16 v[214:215], v199 offset:8192
	ds_read_b64_tr_b16 v[216:217], v199 offset:10240
	ds_read_b64_tr_b16 v[218:219], v199 offset:12288
	ds_read_b64_tr_b16 v[220:221], v199 offset:14336
	v_exp_f32_e32 v98, v98
	v_exp_f32_e32 v99, v99
	v_add_f32_e32 v0, v81, v0
	v_mfma_f32_32x32x16_bf16 v[64:79], v[230:233], v[116:119], v[64:79]
	ds_read_b128 v[230:233], v205 offset:32768
	v_exp_f32_e32 v100, v100
	v_exp_f32_e32 v101, v101
	v_add_f32_e32 v0, v82, v0
	v_mfma_f32_32x32x16_bf16 v[48:63], v[234:237], v[116:119], v[48:63]
	s_waitcnt lgkmcnt(14)
	ds_read_b128 v[234:237], v205 offset:40960
	v_exp_f32_e32 v102, v102
	v_exp_f32_e32 v103, v103
	v_add_f32_e32 v0, v83, v0
	s_waitcnt lgkmcnt(12)
	v_mfma_f32_32x32x16_bf16 v[64:79], v[238:241], v[120:123], v[64:79]
	v_exp_f32_e32 v104, v104
	v_exp_f32_e32 v105, v105
	v_add_f32_e32 v0, v84, v0
	v_mfma_f32_32x32x16_bf16 v[48:63], v[242:245], v[120:123], v[48:63]
	v_exp_f32_e32 v106, v106
	v_exp_f32_e32 v107, v107
	v_add_f32_e32 v0, v85, v0
	v_mfma_f32_32x32x16_bf16 v[64:79], v[246:249], v[124:127], v[64:79]
	v_exp_f32_e32 v108, v108
	v_exp_f32_e32 v109, v109
	v_add_f32_e32 v0, v86, v0
	v_mfma_f32_32x32x16_bf16 v[48:63], v[250:253], v[124:127], v[48:63]
	v_exp_f32_e32 v110, v110
	v_exp_f32_e32 v111, v111
	v_add_f32_e32 v0, v87, v0
	s_waitcnt lgkmcnt(0)
	v_mfma_f32_32x32x16_bf16 v[64:79], v[222:225], v[128:131], v[64:79]
	ds_read_b64_tr_b16 v[238:239], v199 offset:512
	ds_read_b64_tr_b16 v[240:241], v199 offset:2560
	ds_read_b64_tr_b16 v[242:243], v199 offset:4608
	ds_read_b64_tr_b16 v[244:245], v199 offset:6656
	v_cvt_pk_bf16_f32 v156, v96, v97
	v_cvt_pk_bf16_f32 v157, v98, v99
	v_cvt_pk_bf16_f32 v158, v100, v101
	v_cvt_pk_bf16_f32 v159, v102, v103
	v_add_f32_e32 v0, v88, v0
	v_add_f32_e32 v0, v89, v0
	v_mfma_f32_32x32x16_bf16 v[48:63], v[226:229], v[128:131], v[48:63]
	v_cvt_pk_bf16_f32 v160, v104, v105
	v_cvt_pk_bf16_f32 v161, v106, v107
	v_cvt_pk_bf16_f32 v162, v108, v109
	v_cvt_pk_bf16_f32 v163, v110, v111
	v_add_f32_e32 v0, v90, v0
	v_add_f32_e32 v0, v91, v0
	v_mfma_f32_32x32x16_bf16 v[64:79], v[230:233], v[132:135], v[64:79]
	ds_read_b64_tr_b16 v[246:247], v199 offset:8704
	ds_read_b64_tr_b16 v[248:249], v199 offset:10752
	ds_read_b64_tr_b16 v[250:251], v199 offset:12800
	ds_read_b64_tr_b16 v[252:253], v199 offset:14848
	v_add_f32_e32 v0, v92, v0
	v_add_f32_e32 v0, v93, v0
	v_add_f32_e32 v0, v94, v0
	v_add_f32_e32 v0, v95, v0
	v_add_f32_e32 v0, v96, v0
	v_mfma_f32_32x32x16_bf16 v[48:63], v[234:237], v[132:135], v[48:63]
	v_add_f32_e32 v0, v97, v0
	v_add_f32_e32 v0, v98, v0
	v_add_f32_e32 v0, v99, v0
	v_add_f32_e32 v0, v100, v0
	v_add_f32_e32 v0, v101, v0
	s_or_b64 exec, exec, s[2:3]
	s_cmp_ge_u32 s79, s97
	s_cselect_b64 s[2:3], -1, 0
	s_and_b64 vcc, exec, s[2:3]
	s_cbranch_vccnz .Lfast96b_nl
	global_load_dwordx4 v[144:147], v14, s[84:85]
	global_load_dwordx4 v[148:151], v15, s[76:77]
	s_and_saveexec_b64 s[14:15], s[8:9]
	s_cbranch_execz .Lfast96b_k2
	global_load_dwordx4 v[136:139], v188, s[76:77]

; #define SBAR() __builtin_amdgcn_sched_barrier(0)
; template <int D0> __device__ __forceinline__ void pv_one(f32x16& od, int vb, bf16x8 pa0, bf16x8 pa1, bf16x8 pa2, bf16x8 pa3) {
;   const s16x4 l0 = tr_read<v_rd_off(D0, 0, 0)>(vb), h0 = tr_read<v_rd_off(D0, 0, 1)>(vb), l1 = tr_read<v_rd_off(D0, 1, 0)>(vb), h1 = tr_read<v_rd_off(D0, 1, 1)>(vb);
;   const s16x4 l2 = tr_read<v_rd_off(D0, 2, 0)>(vb), h2 = tr_read<v_rd_off(D0, 2, 1)>(vb), l3 = tr_read<v_rd_off(D0, 3, 0)>(vb), h3 = tr_read<v_rd_off(D0, 3, 1)>(vb);
;   asm volatile("s_waitcnt lgkmcnt(0)" ::: "memory"); SBAR();
;     ...
;   od = __builtin_amdgcn_mfma_f32_32x32x16_bf16(pa0, PK(l0, h0), od, 0, 0, 0);
;   od = __builtin_amdgcn_mfma_f32_32x32x16_bf16(pa1, PK(l1, h1), od, 0, 0, 0);
;   od = __builtin_amdgcn_mfma_f32_32x32x16_bf16(pa2, PK(l2, h2), od, 0, 0, 0);
;   od = __builtin_amdgcn_mfma_f32_32x32x16_bf16(pa3, PK(l3, h3), od, 0, 0, 0);
;     ...
; }
.Lfast96b_nl:
	s_and_saveexec_b64 s[14:15], s[10:11]
	s_waitcnt lgkmcnt(0)
	v_mfma_f32_32x32x16_bf16 v[32:47], v[10:13], v[206:209], v[32:47]
	v_add_f32_e32 v0, v102, v0
	v_exp_f32_e32 v64, v64
	v_exp_f32_e32 v65, v65
	v_mfma_f32_32x32x16_bf16 v[32:47], v[152:155], v[210:213], v[32:47]
	v_add_f32_e32 v0, v103, v0
	v_exp_f32_e32 v66, v66
	v_exp_f32_e32 v67, v67
	v_mfma_f32_32x32x16_bf16 v[32:47], v[156:159], v[214:217], v[32:47]
	v_add_f32_e32 v0, v104, v0
	v_add_f32_e32 v0, v105, v0
	v_exp_f32_e32 v68, v68
	v_exp_f32_e32 v69, v69
	v_mfma_f32_32x32x16_bf16 v[32:47], v[160:163], v[218:221], v[32:47]
	v_add_f32_e32 v0, v106, v0
	v_exp_f32_e32 v70, v70
	v_exp_f32_e32 v71, v71
	v_mfma_f32_32x32x16_bf16 v[16:31], v[10:13], v[238:241], v[16:31]
	v_add_f32_e32 v0, v107, v0
	v_exp_f32_e32 v72, v72
	v_exp_f32_e32 v73, v73
	v_mfma_f32_32x32x16_bf16 v[16:31], v[152:155], v[242:245], v[16:31]
	v_add_f32_e32 v0, v108, v0
	v_add_f32_e32 v0, v109, v0
	v_exp_f32_e32 v74, v74
	v_exp_f32_e32 v75, v75
	v_mfma_f32_32x32x16_bf16 v[16:31], v[156:159], v[246:249], v[16:31]
	v_add_f32_e32 v0, v110, v0
	v_exp_f32_e32 v76, v76
	v_exp_f32_e32 v77, v77
	v_mfma_f32_32x32x16_bf16 v[16:31], v[160:163], v[250:253], v[16:31]
	v_add_f32_e32 v0, v111, v0
	v_exp_f32_e32 v78, v78
	v_exp_f32_e32 v79, v79
	v_add_f32_e32 v186, v186, v0
	s_branch .LBB0_911
